# HGRN chunk loop: 8-lane group-norm butterfly via DPP adds instead of three ds_bpermute round trips (on top of LRU hoist + HGRN chain edits)
# baseline (speedup 1.0000x reference)
.LBB0_679:
	v_mul_f32_e32 v0, 0x3fb8aa3b, v0
	v_exp_f32_e32 v14, v0
	v_mul_f32_e32 v0, 0x3fb8aa3b, v2
	v_exp_f32_e32 v12, v0
	v_mul_f32_e32 v0, 0x3fb8aa3b, v4
	v_exp_f32_e32 v10, v0
	v_mul_f32_e32 v0, 0x3fb8aa3b, v6
	v_exp_f32_e32 v8, v0
	v_mul_f32_e32 v0, 0x3fb8aa3b, v16
	v_exp_f32_e32 v6, v0
	v_mul_f32_e32 v0, 0x3fb8aa3b, v78
	v_exp_f32_e32 v4, v0
	v_mul_f32_e32 v0, 0x3fb8aa3b, v79
	v_lshl_add_u64 v[78:79], s[50:51], 0, v[140:141]
	s_mov_b64 s[6:7], 0x14711c00
	v_exp_f32_e32 v2, v0
	v_mul_f32_e32 v0, 0x3fb8aa3b, v80
	v_lshl_add_u64 v[80:81], v[78:79], 0, s[6:7]
	s_mov_b32 s6, 0x14711000
	v_add_co_u32_e32 v78, vcc, s6, v78
	v_pk_mul_f32 v[48:49], v[14:15], v[48:49] op_sel_hi:[0,1]
	s_nop 0
	v_addc_co_u32_e32 v79, vcc, 0, v79, vcc
	global_load_dwordx4 v[82:85], v[78:79], off offset:3072
	s_nop 0
	global_load_dwordx4 v[78:81], v[80:81], off offset:16
	s_waitcnt lgkmcnt(0)
	s_barrier
	v_mul_f32_e64 v46, v14, v46
	v_mul_f32_e64 v47, v14, v47
	v_pk_mul_f32 v[76:77], v[12:13], v[76:77] op_sel_hi:[0,1]
	v_pk_mul_f32 v[74:75], v[12:13], v[74:75] op_sel_hi:[0,1]
	v_mul_f32_e64 v68, v10, v68
	v_mul_f32_e64 v69, v10, v69
	v_pk_mul_f32 v[66:67], v[10:11], v[66:67] op_sel_hi:[0,1]
	v_pk_mul_f32 v[60:61], v[8:9], v[60:61] op_sel_hi:[0,1]
	v_mul_f32_e64 v58, v8, v58
	v_mul_f32_e64 v59, v8, v59
	v_pk_mul_f32 v[56:57], v[6:7], v[56:57] op_sel_hi:[0,1]
	v_pk_mul_f32 v[54:55], v[6:7], v[54:55] op_sel_hi:[0,1]
	v_pk_mul_f32 v[52:53], v[4:5], v[52:53] op_sel_hi:[0,1]
	v_pk_mul_f32 v[50:51], v[4:5], v[50:51] op_sel_hi:[0,1]
	v_pk_mul_f32 v[72:73], v[2:3], v[72:73] op_sel_hi:[0,1]
	v_pk_mul_f32 v[70:71], v[2:3], v[70:71] op_sel_hi:[0,1]
	v_exp_f32_e32 v0, v0
	s_nop 0
	v_add_u32_e32 v2, 0x8c00, v202
	v_pk_mul_f32 v[64:65], v[0:1], v[64:65] op_sel_hi:[0,1]
	v_pk_mul_f32 v[62:63], v[0:1], v[62:63] op_sel_hi:[0,1]
	v_add_u32_e32 v0, 0x8800, v202
	v_and_b32_e32 v4, 64, v177
	v_add_u32_e32 v4, 64, v4
	s_mov_b32 s0, 0x25f91000
	s_add_i32 s5, s5, -1
	s_mov_b64 s[6:7], 0x20000
	v_lshl_add_u64 v[132:133], v[132:133], 0, s[8:9]
	v_lshl_add_u64 v[134:135], v[134:135], 0, s[8:9]
	v_lshl_add_u64 v[136:137], v[136:137], 0, s[8:9]
	v_lshl_add_u64 v[140:141], v[140:141], 0, s[86:87]
	s_cmp_lg_u32 s5, 0
	s_nop 1
	ds_read_b128 v[218:221], v160
	ds_read_b128 v[222:225], v124
	ds_read_b128 v[226:229], v125
	ds_read_b128 v[240:243], v193
	ds_read_b128 v[244:247], v126
	ds_read_b128 v[248:251], v160 offset:64
	ds_read_b128 v[144:147], v124 offset:64
	s_waitcnt lgkmcnt(5)
	v_mfma_f32_16x16x32_bf16 v[86:89], v[218:221], v[222:225], 0
	ds_read_b128 v[180:183], v125 offset:64
	s_waitcnt lgkmcnt(5)
	v_mfma_f32_16x16x32_bf16 v[90:93], v[218:221], v[226:229], 0
	ds_read_b128 v[222:225], v193 offset:64
	s_waitcnt lgkmcnt(5)
	v_mfma_f32_16x16x32_bf16 v[94:97], v[218:221], v[240:243], 0
	ds_read_b128 v[226:229], v126 offset:64
	s_waitcnt lgkmcnt(5)
	v_mfma_f32_16x16x32_bf16 v[98:101], v[218:221], v[244:247], 0
	ds_read_b128 v[240:243], v160 offset:128
	ds_read_b128 v[218:221], v124 offset:128
	s_waitcnt lgkmcnt(5)
	v_mfma_f32_16x16x32_bf16 v[86:89], v[248:251], v[144:147], v[86:89]
	ds_read_b128 v[244:247], v125 offset:128
	s_waitcnt lgkmcnt(5)
	v_mfma_f32_16x16x32_bf16 v[90:93], v[248:251], v[180:183], v[90:93]
	ds_read_b128 v[144:147], v193 offset:128
	s_waitcnt lgkmcnt(5)
	v_mfma_f32_16x16x32_bf16 v[94:97], v[248:251], v[222:225], v[94:97]
	ds_read_b128 v[180:183], v126 offset:128
	s_waitcnt lgkmcnt(5)
	v_mfma_f32_16x16x32_bf16 v[98:101], v[248:251], v[226:229], v[98:101]
	ds_read_b128 v[222:225], v160 offset:192
	ds_read_b128 v[248:251], v124 offset:192
	s_waitcnt lgkmcnt(5)
	v_mfma_f32_16x16x32_bf16 v[86:89], v[240:243], v[218:221], v[86:89]
	ds_read_b128 v[226:229], v125 offset:192
	s_waitcnt lgkmcnt(5)
	v_mfma_f32_16x16x32_bf16 v[90:93], v[240:243], v[244:247], v[90:93]
	ds_read_b128 v[218:221], v193 offset:192
	s_waitcnt lgkmcnt(5)
	v_mfma_f32_16x16x32_bf16 v[94:97], v[240:243], v[144:147], v[94:97]
	ds_read_b128 v[244:247], v126 offset:192
	s_waitcnt lgkmcnt(5)
	v_mfma_f32_16x16x32_bf16 v[98:101], v[240:243], v[180:183], v[98:101]
	ds_read_b128 v[144:147], v161
	ds_read_b128 v[240:243], v128 offset:53248
	s_waitcnt lgkmcnt(5)
	v_mfma_f32_16x16x32_bf16 v[86:89], v[222:225], v[248:251], v[86:89]
	ds_read_b128 v[180:183], v127 offset:53248
	s_waitcnt lgkmcnt(5)
	v_mfma_f32_16x16x32_bf16 v[90:93], v[222:225], v[226:229], v[90:93]
	ds_read_b128 v[248:251], v129 offset:53248
	s_waitcnt lgkmcnt(5)
	v_mfma_f32_16x16x32_bf16 v[94:97], v[222:225], v[218:221], v[94:97]
	ds_read_b128 v[226:229], v130 offset:53248
	s_waitcnt lgkmcnt(5)
	v_mfma_f32_16x16x32_bf16 v[98:101], v[222:225], v[244:247], v[98:101]
	ds_read_b128 v[218:221], v161 offset:64
	ds_read_b128 v[222:225], v128 offset:53312
	s_waitcnt lgkmcnt(5)
	v_mfma_f32_16x16x32_bf16 v[86:89], v[144:147], v[240:243], v[86:89]
	ds_read_b128 v[244:247], v127 offset:53312
	s_waitcnt lgkmcnt(5)
	v_mfma_f32_16x16x32_bf16 v[90:93], v[144:147], v[180:183], v[90:93]
	ds_read_b128 v[240:243], v129 offset:53312
	s_waitcnt lgkmcnt(5)
	v_mfma_f32_16x16x32_bf16 v[94:97], v[144:147], v[248:251], v[94:97]
	ds_read_b128 v[180:183], v130 offset:53312
	s_waitcnt lgkmcnt(5)
	v_mfma_f32_16x16x32_bf16 v[98:101], v[144:147], v[226:229], v[98:101]
	ds_read_b128 v[248:251], v120 offset:53248
	ds_read_b128 v[144:147], v120 offset:53312
	s_waitcnt lgkmcnt(5)
	v_mfma_f32_16x16x32_bf16 v[86:89], v[218:221], v[222:225], v[86:89]
	ds_read_b128 v[226:229], v131 offset:34816
	s_waitcnt lgkmcnt(5)
	v_mfma_f32_16x16x32_bf16 v[90:93], v[218:221], v[244:247], v[90:93]
	ds_read_b128 v[222:225], v195 offset:34816
	s_waitcnt lgkmcnt(5)
	v_mfma_f32_16x16x32_bf16 v[94:97], v[218:221], v[240:243], v[94:97]
	ds_read_b128 v[244:247], v196 offset:34816
	s_waitcnt lgkmcnt(5)
	v_mfma_f32_16x16x32_bf16 v[98:101], v[218:221], v[180:183], v[98:101]
	ds_read_b128 v[240:243], v197 offset:34816
	ds_read_b128 v[218:221], v198 offset:34816
	ds_read_b128 v[180:183], v199 offset:34816
	s_waitcnt lgkmcnt(5)
	v_mfma_f32_16x16x32_bf16 v[46:49], v[248:251], v[226:229], v[46:49]
	ds_read_b128 v[226:229], v200 offset:34816
	s_waitcnt lgkmcnt(5)
	v_mfma_f32_16x16x32_bf16 v[74:77], v[248:251], v[222:225], v[74:77]
	ds_read_b128 v[222:225], v201 offset:34816
	s_waitcnt lgkmcnt(5)
	v_mfma_f32_16x16x32_bf16 v[66:69], v[248:251], v[244:247], v[66:69]
	ds_read_b128 v[244:247], v131 offset:34880
	s_waitcnt lgkmcnt(5)
	v_mfma_f32_16x16x32_bf16 v[58:61], v[248:251], v[240:243], v[58:61]
	ds_read_b128 v[240:243], v195 offset:34880
	s_waitcnt lgkmcnt(5)
	v_mfma_f32_16x16x32_bf16 v[54:57], v[248:251], v[218:221], v[54:57]
	ds_read_b128 v[218:221], v196 offset:34880
	s_waitcnt lgkmcnt(5)
	v_mfma_f32_16x16x32_bf16 v[50:53], v[248:251], v[180:183], v[50:53]
	ds_read_b128 v[180:183], v197 offset:34880
	s_waitcnt lgkmcnt(5)
	v_mfma_f32_16x16x32_bf16 v[70:73], v[248:251], v[226:229], v[70:73]
	ds_read_b128 v[226:229], v198 offset:34880
	s_waitcnt lgkmcnt(5)
	v_mfma_f32_16x16x32_bf16 v[62:65], v[248:251], v[222:225], v[62:65]
	ds_read_b128 v[248:251], v199 offset:34880
	s_waitcnt lgkmcnt(5)
	v_mfma_f32_16x16x32_bf16 v[46:49], v[144:147], v[244:247], v[46:49]
	ds_read_b128 v[222:225], v200 offset:34880
	s_waitcnt lgkmcnt(5)
	v_mfma_f32_16x16x32_bf16 v[74:77], v[144:147], v[240:243], v[74:77]
	ds_read_b128 v[244:247], v201 offset:34880
	s_waitcnt lgkmcnt(5)
	v_mfma_f32_16x16x32_bf16 v[66:69], v[144:147], v[218:221], v[66:69]
	s_waitcnt lgkmcnt(4)
	v_mfma_f32_16x16x32_bf16 v[58:61], v[144:147], v[180:183], v[58:61]
	s_waitcnt lgkmcnt(3)
	v_mfma_f32_16x16x32_bf16 v[54:57], v[144:147], v[226:229], v[54:57]
	s_waitcnt lgkmcnt(2)
	v_mfma_f32_16x16x32_bf16 v[50:53], v[144:147], v[248:251], v[50:53]
	s_waitcnt lgkmcnt(1)
	v_mfma_f32_16x16x32_bf16 v[70:73], v[144:147], v[222:225], v[70:73]
	s_waitcnt lgkmcnt(0)
	v_mfma_f32_16x16x32_bf16 v[62:65], v[144:147], v[244:247], v[62:65]
	s_waitcnt lgkmcnt(0)
	s_barrier
	ds_write2_b32 v0, v86, v90 offset1:16
	ds_write2_b32 v2, v88, v92 offset0:8 offset1:24
	ds_write2_b32 v0, v94, v87 offset0:32 offset1:132
	ds_write2_b32 v0, v91, v95 offset0:148 offset1:164
	ds_write2_b32 v2, v96, v89 offset0:40 offset1:140
	ds_write2_b32 v2, v93, v97 offset0:156 offset1:172
	v_add_u32_e32 v0, 0x8800, v203
	ds_write2_b32 v0, v98, v99 offset1:132
	v_add_u32_e32 v0, 0x8c00, v203
	ds_write2_b32 v0, v100, v101 offset0:8 offset1:140
	s_waitcnt lgkmcnt(0)
	s_barrier
	ds_read_b128 v[98:101], v207 offset:34816
	ds_read_b128 v[90:93], v207 offset:34832
	ds_read_b128 v[94:97], v207 offset:34848
	ds_read_b128 v[86:89], v207 offset:34864
	s_waitcnt lgkmcnt(3)
	v_mov_b32_e32 v220, v99
	s_waitcnt lgkmcnt(2)
	v_mov_b32_e32 v221, v91
	v_mov_b32_e32 v218, v98
	v_mov_b32_e32 v219, v90
	v_pk_mul_f32 v[220:221], v[220:221], v[220:221]
	s_waitcnt lgkmcnt(1)
	v_mov_b32_e32 v222, v95
	v_pk_fma_f32 v[218:219], v[218:219], v[218:219], v[220:221]
	v_mov_b32_e32 v220, v100
	v_mov_b32_e32 v221, v92
	v_pk_fma_f32 v[218:219], v[220:221], v[220:221], v[218:219]
	v_mov_b32_e32 v220, v101
	v_mov_b32_e32 v221, v93
	s_waitcnt lgkmcnt(0)
	v_mov_b32_e32 v223, v87
	v_pk_fma_f32 v[218:219], v[220:221], v[220:221], v[218:219]
	v_mov_b32_e32 v220, v94
	v_mov_b32_e32 v221, v86
	v_pk_mul_f32 v[222:223], v[222:223], v[222:223]
	v_xor_b32_e32 v2, 1, v177
	v_pk_fma_f32 v[220:221], v[220:221], v[220:221], v[222:223]
	v_mov_b32_e32 v222, v96
	v_mov_b32_e32 v223, v88
	v_pk_fma_f32 v[220:221], v[222:223], v[222:223], v[220:221]
	v_mov_b32_e32 v222, v97
	v_mov_b32_e32 v223, v89
	v_pk_fma_f32 v[220:221], v[222:223], v[222:223], v[220:221]
	v_add_f32_e32 v0, v218, v219
	v_cmp_lt_i32_e32 vcc, v2, v4
	v_add_f32_e32 v0, v0, v220
	v_add_f32_e32 v0, v0, v221
	s_nop 1
	v_add_f32_dpp v0, v0, v0 quad_perm:[1,0,3,2] row_mask:0xf bank_mask:0xf
	s_waitcnt vmcnt(1)
	v_lshlrev_b32_e32 v218, 16, v82
	s_waitcnt lgkmcnt(0)
	v_add_f32_dpp v0, v0, v0 quad_perm:[2,3,0,1] row_mask:0xf bank_mask:0xf
	s_nop 1
	v_add_f32_dpp v0, v0, v0 row_half_mirror row_mask:0xf bank_mask:0xf
	v_fmamk_f32 v0, v0, 0x3c000000, v143
	v_cmp_gt_f32_e32 vcc, s90, v0
	v_mul_f32_e32 v2, 0x4b800000, v0
	s_nop 0
	v_cndmask_b32_e32 v0, v0, v2, vcc
	v_rsq_f32_e32 v0, v0
	s_nop 0
	v_mul_f32_e32 v2, 0x45800000, v0
	v_cndmask_b32_e32 v0, v0, v2, vcc
	v_mul_f32_e32 v2, 0xbfb8aa3b, v218
	v_exp_f32_e32 v2, v2
	v_mul_f32_e32 v219, v98, v0
	v_and_b32_e32 v98, 0xffff0000, v82
	v_mul_f32_e32 v99, v99, v0
	v_add_f32_e32 v2, 1.0, v2
	v_rcp_f32_e32 v102, v2
	v_mul_f32_e32 v2, 0xbfb8aa3b, v98
	v_exp_f32_e32 v2, v2
	v_mul_f32_e32 v95, v95, v0
	v_pk_mul_f32 v[218:219], v[102:103], v[218:219]
	v_mul_f32_e32 v91, v91, v0
	v_add_f32_e32 v2, 1.0, v2
	v_rcp_f32_e32 v2, v2
	v_mul_f32_e32 v4, v218, v219
	v_mul_f32_e32 v87, v87, v0
	v_pk_mul_f32 v[98:99], v[2:3], v[98:99]
	s_nop 0
	v_mul_f32_e32 v2, v98, v99
	v_mul_f32_e32 v99, v94, v0
	s_waitcnt vmcnt(0)
	v_lshlrev_b32_e32 v98, 16, v78
	v_and_b32_e32 v94, 0xffff0000, v78
	v_cvt_pk_bf16_f32 v82, v4, v2
	v_mul_f32_e32 v2, 0xbfb8aa3b, v98
	v_mul_f32_e32 v4, 0xbfb8aa3b, v94
	v_exp_f32_e32 v2, v2
	v_exp_f32_e32 v4, v4
	v_add_f32_e32 v2, 1.0, v2
	v_add_f32_e32 v4, 1.0, v4
	v_rcp_f32_e32 v110, v2
	v_rcp_f32_e32 v10, v4
	v_pk_mul_f32 v[98:99], v[110:111], v[98:99]
	v_pk_mul_f32 v[94:95], v[10:11], v[94:95]
	v_mul_f32_e32 v2, v98, v99
	v_mul_f32_e32 v4, v94, v95
	v_lshlrev_b32_e32 v94, 16, v83
	v_cvt_pk_bf16_f32 v78, v2, v4
	v_mul_f32_e32 v2, 0xbfb8aa3b, v94
	v_exp_f32_e32 v2, v2
	v_mul_f32_e32 v95, v100, v0
	v_add_f32_e32 v2, 1.0, v2
	v_rcp_f32_e32 v104, v2
	s_nop 0
	v_pk_mul_f32 v[94:95], v[104:105], v[94:95]
	s_nop 0
	v_mul_f32_e32 v2, v94, v95
	v_and_b32_e32 v94, 0xffff0000, v83
	v_mul_f32_e32 v4, 0xbfb8aa3b, v94
	v_exp_f32_e32 v4, v4
	v_mul_f32_e32 v95, v101, v0
	v_add_f32_e32 v4, 1.0, v4
	v_rcp_f32_e32 v4, v4
	s_nop 0
	v_pk_mul_f32 v[94:95], v[4:5], v[94:95]
	s_nop 0
	v_mul_f32_e32 v4, v94, v95
	v_lshlrev_b32_e32 v94, 16, v79
	v_cvt_pk_bf16_f32 v83, v2, v4
	v_mul_f32_e32 v2, 0xbfb8aa3b, v94
	v_exp_f32_e32 v2, v2
	v_mul_f32_e32 v95, v96, v0
	v_add_f32_e32 v2, 1.0, v2
	v_rcp_f32_e32 v112, v2
	s_nop 0
	v_pk_mul_f32 v[94:95], v[112:113], v[94:95]
	s_nop 0
	v_mul_f32_e32 v2, v94, v95
	v_and_b32_e32 v94, 0xffff0000, v79
	v_mul_f32_e32 v4, 0xbfb8aa3b, v94
	v_exp_f32_e32 v4, v4
	v_mul_f32_e32 v95, v97, v0
	v_add_f32_e32 v4, 1.0, v4
	v_rcp_f32_e32 v12, v4
	s_nop 0
	v_pk_mul_f32 v[94:95], v[12:13], v[94:95]
	s_nop 0
	v_mul_f32_e32 v4, v94, v95
	v_mul_f32_e32 v95, v90, v0
	v_lshlrev_b32_e32 v94, 16, v84
	v_and_b32_e32 v90, 0xffff0000, v84
	v_cvt_pk_bf16_f32 v79, v2, v4
	v_mul_f32_e32 v2, 0xbfb8aa3b, v94
	v_mul_f32_e32 v4, 0xbfb8aa3b, v90
	v_exp_f32_e32 v2, v2
	v_exp_f32_e32 v4, v4
	v_add_f32_e32 v2, 1.0, v2
	v_add_f32_e32 v4, 1.0, v4
	v_rcp_f32_e32 v106, v2
	v_rcp_f32_e32 v6, v4
	v_pk_mul_f32 v[94:95], v[106:107], v[94:95]
	v_pk_mul_f32 v[90:91], v[6:7], v[90:91]
	v_mul_f32_e32 v2, v94, v95
	v_mul_f32_e32 v4, v90, v91
	v_mul_f32_e32 v91, v86, v0
	v_lshlrev_b32_e32 v90, 16, v80
	v_and_b32_e32 v86, 0xffff0000, v80
	v_cvt_pk_bf16_f32 v84, v2, v4
	v_mul_f32_e32 v2, 0xbfb8aa3b, v90
	v_mul_f32_e32 v4, 0xbfb8aa3b, v86
	v_exp_f32_e32 v2, v2
	v_exp_f32_e32 v4, v4
	v_mov_b32_e32 v6, v211
	v_add_f32_e32 v2, 1.0, v2
	v_add_f32_e32 v4, 1.0, v4
	v_rcp_f32_e32 v114, v2
	v_rcp_f32_e32 v14, v4
	v_pk_mul_f32 v[90:91], v[114:115], v[90:91]
	v_pk_mul_f32 v[86:87], v[14:15], v[86:87]
	v_mul_f32_e32 v2, v90, v91
	v_mul_f32_e32 v4, v86, v87
	v_lshlrev_b32_e32 v86, 16, v85
	v_cvt_pk_bf16_f32 v80, v2, v4
	v_mul_f32_e32 v2, 0xbfb8aa3b, v86
	v_exp_f32_e32 v2, v2
	v_mul_f32_e32 v87, v92, v0
	v_add_f32_e32 v2, 1.0, v2
	v_rcp_f32_e32 v108, v2
	s_nop 0
	v_pk_mul_f32 v[86:87], v[108:109], v[86:87]
	s_nop 0
	v_mul_f32_e32 v2, v86, v87
	v_and_b32_e32 v86, 0xffff0000, v85
	v_mul_f32_e32 v4, 0xbfb8aa3b, v86
	v_exp_f32_e32 v4, v4
	v_mul_f32_e32 v87, v93, v0
	v_add_f32_e32 v4, 1.0, v4
	v_rcp_f32_e32 v8, v4
	s_nop 0
	v_pk_mul_f32 v[86:87], v[8:9], v[86:87]
	s_nop 0
	v_mul_f32_e32 v4, v86, v87
	v_lshlrev_b32_e32 v86, 16, v81
	v_cvt_pk_bf16_f32 v85, v2, v4
	v_mul_f32_e32 v2, 0xbfb8aa3b, v86
	v_exp_f32_e32 v2, v2
	v_mul_f32_e32 v87, v88, v0
	v_mov_b32_e32 v4, v210
	v_add_f32_e32 v2, 1.0, v2
	v_rcp_f32_e32 v116, v2
	s_nop 0
	v_pk_mul_f32 v[86:87], v[116:117], v[86:87]
	s_nop 0
	v_mul_f32_e32 v2, v86, v87
	v_and_b32_e32 v86, 0xffff0000, v81
	v_mul_f32_e32 v87, v89, v0
	v_mul_f32_e32 v0, 0xbfb8aa3b, v86
	v_exp_f32_e32 v0, v0
	s_nop 0
	v_add_f32_e32 v0, 1.0, v0
	v_rcp_f32_e32 v16, v0
	s_nop 0
	v_pk_mul_f32 v[86:87], v[16:17], v[86:87]
	s_nop 0
	v_mul_f32_e32 v0, v86, v87
	v_lshl_add_u64 v[86:87], s[50:51], 0, v[138:139]
	v_add_co_u32_e32 v86, vcc, s0, v86
	v_cvt_pk_bf16_f32 v81, v2, v0
	v_lshl_add_u64 v[138:139], v[138:139], 0, s[6:7]
	s_nop 0
	v_addc_co_u32_e32 v87, vcc, 0, v87, vcc
	global_store_dwordx4 v[86:87], v[82:85], off
	global_store_dwordx4 v[86:87], v[78:81], off offset:16
	v_mov_b32_e32 v0, v208
	v_mov_b32_e32 v2, v209
	v_mov_b32_e32 v16, v212
	v_mov_b32_e32 v78, v213
	v_mov_b32_e32 v79, v214
	v_mov_b32_e32 v80, v215
	s_cbranch_scc0 .LBB0_682
